# speedup vs baseline: 1.1392x; 1.0090x over previous
; DEV int otid() { int t = threadIdx.x; asm volatile("" : "+v"(t)); return t; }
;   const int tid = otid(), lane = tid & 63, w = __builtin_amdgcn_readfirstlane(tid >> 6), wm = w >> 1, wn = w & 1, r32 = lane & 31, hh = lane >> 5;
;   f32x16 acc[MI / 2][2][2];
; #pragma unroll
;   for (int h = 0; h < MI / 2; ++h) { acc[h][0][0] = zero16(); acc[h][0][1] = zero16(); acc[h][1][0] = zero16(); acc[h][1][1] = zero16(); }
;   const int lrow = lane >> 2, lp = (lane & 3) ^ ((lane >> 4) & 3);
;   const bf16_t* ag = uni_ptr(A + (size_t)m0 * lda + kbeg);
;   const bf16_t* bg = uni_ptr(Bt + (size_t)n0 * ldb + kbeg);
;   const unsigned voffa = ((unsigned)lrow * (unsigned)lda + (unsigned)lp * 8u) * 2u;
;   const unsigned voffb = ((unsigned)lrow * (unsigned)ldb + (unsigned)lp * 8u) * 2u;
;   const int nk = (kend - kbeg) >> 5;
;   if (!pre) {
;     asm volatile("s_waitcnt vmcnt(0)" ::: "memory");
;     g2_issue<MI>(ag, bg, lda, ldb, voffa, voffb, lds, w);
;     if (nk > 1) g2_issue<MI>(ag + 32, bg + 32, lda, ldb, voffa, voffb, lds + G2_STAGE, w);
;   }
;   const int key = (r32 >> 2) & 3;
;   const int aoff = (wm * (MI * 32) + r32) * 64;
;   const int boff = 16384 + (wn * 64 + r32) * 64;
;   const int p0 = ((0 + hh) ^ key) * 16, p1 = ((2 + hh) ^ key) * 16;
;   const unsigned lbase = (unsigned)(size_t)lds;
;   const unsigned la0 = lbase + aoff + p0, la1 = lbase + aoff + p1, lb0 = lbase + boff + p0, lb1 = lbase + boff + p1;
;   int stg = 0;
.LBB0_121:
	v_mov_b32_e32 v2, v192
	v_readlane_b32 s0, v239, 24
	v_readfirstlane_b32 s12, v2
	s_ashr_i32 s4, s12, 6
	s_add_u32 s6, s26, s0
	s_addc_u32 s7, s27, 0
	v_readlane_b32 s0, v239, 25
	v_lshlrev_b32_e32 v4, 4, v2
	s_add_u32 s10, s28, s0
	v_bitop3_b32 v4, v4, 48, v2 bitop3:0x48
	v_lshlrev_b32_e32 v5, 10, v2
	s_mov_b32 s0, 0xf000
	s_addc_u32 s11, s30, 0
	v_and_or_b32 v70, v5, s0, v4
	s_lshl_b32 s0, s4, 5
	s_ashr_i32 s1, s0, 31
	s_lshl_b32 s5, s4, 1
	s_lshl_b64 s[2:3], s[0:1], 12
	s_add_u32 s0, s6, s2
	s_addc_u32 s1, s7, s3
	s_or_b32 s9, s5, 1
	s_lshl_b32 s8, s4, 11
	s_lshl_b32 s4, s9, 4
	s_ashr_i32 s5, s4, 31
	s_lshl_b64 s[4:5], s[4:5], 12
	s_add_u32 s6, s6, s4
	s_addc_u32 s7, s7, s5
	s_lshl_b32 s9, s9, 10
	s_waitcnt vmcnt(0)
	s_add_u32 s2, s10, s2
	s_mov_b32 m0, s8
	s_nop 0
	global_load_lds_dwordx4 v70, s[0:1]
	s_addc_u32 s3, s11, s3
	s_add_i32 s13, s8, 0x4000
	s_mov_b32 m0, s9
	s_nop 0
	global_load_lds_dwordx4 v70, s[6:7]
	s_add_u32 s4, s10, s4
	s_mov_b32 m0, s13
	s_nop 0
	global_load_lds_dwordx4 v70, s[2:3]
	s_addc_u32 s5, s11, s5
	s_add_i32 s10, s9, 0x4000
	s_mov_b32 m0, s10
	s_nop 0
	global_load_lds_dwordx4 v70, s[4:5]
	s_add_u32 s10, s0, 64
	s_addc_u32 s11, s1, 0
	s_add_i32 s13, s8, 0x6000
	s_add_u32 s6, s6, 64
	s_mov_b32 m0, s13
	s_nop 0
	global_load_lds_dwordx4 v70, s[10:11]
	s_addc_u32 s7, s7, 0
	s_add_i32 s10, s9, 0x6000
	s_mov_b32 m0, s10
	s_nop 0
	global_load_lds_dwordx4 v70, s[6:7]
	s_add_u32 s6, s2, 64
	s_addc_u32 s7, s3, 0
	s_add_i32 s10, s8, 0xa000
	s_add_u32 s4, s4, 64
	s_mov_b32 m0, s10
	s_nop 0
	global_load_lds_dwordx4 v70, s[6:7]
	s_addc_u32 s5, s5, 0
	s_add_i32 s6, s9, 0xa000
	s_mov_b32 m0, s6
	s_nop 0
	global_load_lds_dwordx4 v70, s[4:5]
	s_ashr_i32 s6, s12, 1
	v_and_b32_e32 v1, 31, v2
	s_andn2_b32 s6, s6, 63
	v_or_b32_e32 v4, s6, v1
	s_and_b32 s7, s12, 64
	v_lshrrev_b32_e32 v3, 5, v2
	v_bfe_u32 v66, v2, 5, 1
	v_bfe_u32 v2, v2, 2, 2
	v_lshlrev_b32_e32 v67, 6, v4
	v_or_b32_e32 v4, s7, v1
	v_lshlrev_b32_e32 v72, 6, v4
	v_bitop3_b32 v3, v3, v2, 1 bitop3:0x6c
	v_bitop3_b32 v2, v66, v2, 2 bitop3:0x36
	v_mov_b32_e32 v34, 0
	v_or_b32_e32 v68, 0x4000, v72
	v_lshlrev_b32_e32 v71, 4, v3
	v_lshlrev_b32_e32 v69, 4, v2
	s_mov_b32 s10, 0
	s_mov_b64 s[4:5], 0
	v_mov_b32_e32 v35, v34
	v_mov_b32_e32 v36, v34
	v_mov_b32_e32 v37, v34
	v_mov_b32_e32 v38, v34
	v_mov_b32_e32 v39, v34
	v_mov_b32_e32 v40, v34
	v_mov_b32_e32 v41, v34
	v_mov_b32_e32 v42, v34
	v_mov_b32_e32 v43, v34
	v_mov_b32_e32 v44, v34
	v_mov_b32_e32 v45, v34
	v_mov_b32_e32 v46, v34
	v_mov_b32_e32 v47, v34
	v_mov_b32_e32 v48, v34
	v_mov_b32_e32 v49, v34
	v_mov_b32_e32 v50, v34
	v_mov_b32_e32 v51, v34
	v_mov_b32_e32 v52, v34
	v_mov_b32_e32 v53, v34
	v_mov_b32_e32 v54, v34
	v_mov_b32_e32 v55, v34
	v_mov_b32_e32 v56, v34
	v_mov_b32_e32 v57, v34
	v_mov_b32_e32 v58, v34
	v_mov_b32_e32 v59, v34
	v_mov_b32_e32 v60, v34
	v_mov_b32_e32 v61, v34
	v_mov_b32_e32 v62, v34
	v_mov_b32_e32 v63, v34
	v_mov_b32_e32 v64, v34
	v_mov_b32_e32 v65, v34
	v_mov_b32_e32 v18, v34
	v_mov_b32_e32 v19, v34
	v_mov_b32_e32 v20, v34
	v_mov_b32_e32 v21, v34
	v_mov_b32_e32 v22, v34
	v_mov_b32_e32 v23, v34
	v_mov_b32_e32 v24, v34
	v_mov_b32_e32 v25, v34
	v_mov_b32_e32 v26, v34
	v_mov_b32_e32 v27, v34
	v_mov_b32_e32 v28, v34
	v_mov_b32_e32 v29, v34
	v_mov_b32_e32 v30, v34
	v_mov_b32_e32 v31, v34
	v_mov_b32_e32 v32, v34
	v_mov_b32_e32 v33, v34
	v_mov_b32_e32 v2, v34
	v_mov_b32_e32 v3, v34
	v_mov_b32_e32 v4, v34
	v_mov_b32_e32 v5, v34
	v_mov_b32_e32 v6, v34
	v_mov_b32_e32 v7, v34
	v_mov_b32_e32 v8, v34
	v_mov_b32_e32 v9, v34
	v_mov_b32_e32 v10, v34
	v_mov_b32_e32 v11, v34
	v_mov_b32_e32 v12, v34
	v_mov_b32_e32 v13, v34
	v_mov_b32_e32 v14, v34
	v_mov_b32_e32 v15, v34
	v_mov_b32_e32 v16, v34
	v_mov_b32_e32 v17, v34
	v_lshlrev_b32_e32 v254, 4, v200
; DEV f32x16 mfma(bf16x8 a, bf16x8 b, f32x16 c) { return __builtin_amdgcn_mfma_f32_32x32x16_bf16(a, b, c, 0, 0, 0); }
;     ...
;   for (int kt = 0; kt < nk; ++kt) {
;     if (kt + 1 < nk) { if (MI == 4) asm volatile("s_waitcnt vmcnt(6)" ::: "memory"); else asm volatile("s_waitcnt vmcnt(4)" ::: "memory"); } else asm volatile("s_waitcnt vmcnt(0)" ::: "memory");
;     __builtin_amdgcn_s_barrier();
;     if (kt + 2 < nk) { int s2 = stg + 2; if (s2 >= 3) s2 -= 3; g2_issue<MI>(ag + (size_t)(kt + 2) * 32, bg + (size_t)(kt + 2) * 32, lda, ldb, voffa, voffb, lds + s2 * G2_STAGE, w); }
;     const unsigned so = (unsigned)(stg * G2_STAGE);
;     __builtin_amdgcn_s_setprio(1);
; #pragma unroll
;     for (int ks = 0; ks < 2; ++ks) {
;       const unsigned aa = (ks ? la1 : la0) + so, bb = (ks ? lb1 : lb0) + so;
;       bf16x8 fb0, fb1, fa0, fa1, fa2, fa3;
;       asm volatile("ds_read_b128 %0, %1" : "=v"(fb0) : "v"(bb));
;       asm volatile("ds_read_b128 %0, %1 offset:2048" : "=v"(fb1) : "v"(bb));
;       asm volatile("ds_read_b128 %0, %1" : "=v"(fa0) : "v"(aa));
;       asm volatile("ds_read_b128 %0, %1 offset:2048" : "=v"(fa1) : "v"(aa));
;       if constexpr (MI == 4) {
;         asm volatile("ds_read_b128 %0, %1 offset:4096" : "=v"(fa2) : "v"(aa));
;         asm volatile("ds_read_b128 %0, %1 offset:6144" : "=v"(fa3) : "v"(aa));
;         __builtin_amdgcn_sched_barrier(0);
;         asm volatile("s_waitcnt lgkmcnt(3)" : "+v"(fb0), "+v"(fb1), "+v"(fa0));
;         acc[0][0][0] = mfma(fa0, fb0, acc[0][0][0]); acc[0][0][1] = mfma(fa0, fb1, acc[0][0][1]); __builtin_amdgcn_sched_barrier(0);
;         asm volatile("s_waitcnt lgkmcnt(2)" : "+v"(fa1));
;         acc[0][1][0] = mfma(fa1, fb0, acc[0][1][0]); acc[0][1][1] = mfma(fa1, fb1, acc[0][1][1]); __builtin_amdgcn_sched_barrier(0);
;         asm volatile("s_waitcnt lgkmcnt(1)" : "+v"(fa2));
;         acc[MI / 2 - 1][0][0] = mfma(fa2, fb0, acc[MI / 2 - 1][0][0]); acc[MI / 2 - 1][0][1] = mfma(fa2, fb1, acc[MI / 2 - 1][0][1]); __builtin_amdgcn_sched_barrier(0);
;         asm volatile("s_waitcnt lgkmcnt(0)" : "+v"(fa3));
;         acc[MI / 2 - 1][1][0] = mfma(fa3, fb0, acc[MI / 2 - 1][1][0]); acc[MI / 2 - 1][1][1] = mfma(fa3, fb1, acc[MI / 2 - 1][1][1]); __builtin_amdgcn_sched_barrier(0);
;       } else {
;         __builtin_amdgcn_sched_barrier(0);
;         asm volatile("s_waitcnt lgkmcnt(1)" : "+v"(fb0), "+v"(fb1), "+v"(fa0));
.LBB0_122:
	s_cmp_gt_i32 s10, 0
	s_cselect_b32 s11, -1, 2
	s_add_i32 s11, s11, s10
	s_add_u32 s14, s0, s4
	s_addc_u32 s15, s1, s5
	s_mulk_i32 s11, 0x6000
	s_add_u32 s12, s14, 0x80
	s_addc_u32 s13, s15, 0
	s_add_i32 s16, s8, s11
	s_cmp_eq_u32 s4, 0
	s_cbranch_scc1 .Lhyt_first_tail
	s_waitcnt vmcnt(0)
	s_barrier
	s_mul_i32 s99, s10, 0x6000
	s_setprio 1
	v_add_u32_e32 v73, s99, v67
	v_add_u32_e32 v90, s99, v68
	v_add_u32_e32 v86, v73, v71
	v_add_u32_e32 v78, v90, v71
	ds_read_b128 v[74:77], v78
	ds_read_b128 v[78:81], v78 offset:2048
	ds_read_b128 v[82:85], v86
	ds_read_b128 v[86:89], v86 offset:2048
	v_add_u32_e32 v238, v90, v69
	v_add_u32_e32 v73, v73, v69
	ds_read_b128 v[180:183], v238
	ds_read_b128 v[184:187], v238 offset:2048
	ds_read_b128 v[188:191], v73
	ds_read_b128 v[242:245], v73 offset:2048
	s_add_i32 s98, s10, 1
	s_cmp_lg_u32 s10, 2
	s_cselect_b32 s98, s98, 0
	s_mul_i32 s98, s98, 0x6000
	s_add_i32 s99, s8, s98
	v_add_u32_e32 v238, s99, v254
	ds_write_b128 v238, v[214:217]
	s_add_i32 s99, s9, s98
	v_add_u32_e32 v255, s99, v254
	ds_write_b128 v255, v[218:221]
	s_cmpk_eq_i32 s4, 0xf80
	s_cbranch_scc1 .Lhyt_noissueE_tail
	s_mov_b32 m0, s16
	s_nop 0
	global_load_lds_dwordx4 v70, s[12:13]
	global_load_dwordx4 v[214:217], v70, s[12:13] offset:64
	s_nop 0
	s_waitcnt lgkmcnt(5)
	s_nop 0
	v_mfma_f32_32x32x16_bf16 v[34:49], v[82:85], v[74:77], v[34:49]
	v_mfma_f32_32x32x16_bf16 v[50:65], v[82:85], v[78:81], v[50:65]
	s_add_u32 s12, s14, 0x10080
	s_addc_u32 s13, s15, 0
	s_add_i32 s14, s9, s11
	s_addk_i32 s11, 0x4000
	s_mov_b32 m0, s14
	s_nop 0
	global_load_lds_dwordx4 v70, s[12:13]
	global_load_dwordx4 v[218:221], v70, s[12:13] offset:64
	s_waitcnt lgkmcnt(4)
	s_nop 0
	v_mfma_f32_32x32x16_bf16 v[18:33], v[86:89], v[74:77], v[18:33]
	v_mfma_f32_32x32x16_bf16 v[2:17], v[86:89], v[78:81], v[2:17]
	s_branch .Lhyt_afterE_tail
.Lhyt_noissueE_tail:
	s_nop 0
	s_waitcnt lgkmcnt(5)
	s_nop 0
	v_mfma_f32_32x32x16_bf16 v[34:49], v[82:85], v[74:77], v[34:49]
	v_mfma_f32_32x32x16_bf16 v[50:65], v[82:85], v[78:81], v[50:65]
	s_waitcnt lgkmcnt(4)
	s_nop 0
	v_mfma_f32_32x32x16_bf16 v[18:33], v[86:89], v[74:77], v[18:33]
	v_mfma_f32_32x32x16_bf16 v[2:17], v[86:89], v[78:81], v[2:17]
.Lhyt_afterE_tail:
	s_nop 0
	s_waitcnt lgkmcnt(3)
	s_nop 0
	v_mfma_f32_32x32x16_bf16 v[34:49], v[188:191], v[180:183], v[34:49]
	v_mfma_f32_32x32x16_bf16 v[50:65], v[188:191], v[184:187], v[50:65]
	s_waitcnt lgkmcnt(2)
	s_nop 0
	v_mfma_f32_32x32x16_bf16 v[18:33], v[242:245], v[180:183], v[18:33]
	v_mfma_f32_32x32x16_bf16 v[2:17], v[242:245], v[184:187], v[2:17]
	s_add_i32 s99, s8, s98
	s_addk_i32 s99, 0x4000
	v_add_u32_e32 v238, s99, v254
	ds_write_b128 v238, v[222:225]
	s_add_i32 s99, s9, s98
	s_addk_i32 s99, 0x4000
	v_add_u32_e32 v255, s99, v254
	ds_write_b128 v255, v[226:229]
	s_branch .Lhyt_odd_tail
.Lhyt_first_tail:
	s_waitcnt vmcnt(4)
	s_barrier
	s_mul_i32 s99, s10, 0x6000
	s_setprio 1
	v_add_u32_e32 v73, s99, v67
	v_add_u32_e32 v90, s99, v68
	v_add_u32_e32 v86, v73, v71
	v_add_u32_e32 v78, v90, v71
	ds_read_b128 v[74:77], v78
	ds_read_b128 v[78:81], v78 offset:2048
	ds_read_b128 v[82:85], v86
	ds_read_b128 v[86:89], v86 offset:2048
	v_add_u32_e32 v238, v90, v69
	v_add_u32_e32 v73, v73, v69
	ds_read_b128 v[180:183], v238
	ds_read_b128 v[184:187], v238 offset:2048
	ds_read_b128 v[188:191], v73
	ds_read_b128 v[242:245], v73 offset:2048
	s_cmpk_eq_i32 s4, 0xf80
	s_cbranch_scc1 .Lhyt_noissueF_tail
	s_mov_b32 m0, s16
	s_nop 0
	global_load_lds_dwordx4 v70, s[12:13]
	global_load_dwordx4 v[214:217], v70, s[12:13] offset:64
	s_nop 0
	s_waitcnt lgkmcnt(5)
	s_nop 0
	v_mfma_f32_32x32x16_bf16 v[34:49], v[82:85], v[74:77], v[34:49]
	v_mfma_f32_32x32x16_bf16 v[50:65], v[82:85], v[78:81], v[50:65]
	s_add_u32 s12, s14, 0x10080
	s_addc_u32 s13, s15, 0
	s_add_i32 s14, s9, s11
	s_addk_i32 s11, 0x4000
	s_mov_b32 m0, s14
	s_nop 0
	global_load_lds_dwordx4 v70, s[12:13]
	global_load_dwordx4 v[218:221], v70, s[12:13] offset:64
	s_waitcnt lgkmcnt(4)
	s_nop 0
	v_mfma_f32_32x32x16_bf16 v[18:33], v[86:89], v[74:77], v[18:33]
	v_mfma_f32_32x32x16_bf16 v[2:17], v[86:89], v[78:81], v[2:17]
	s_branch .Lhyt_afterF_tail

; DEV f32x16 mfma(bf16x8 a, bf16x8 b, f32x16 c) { return __builtin_amdgcn_mfma_f32_32x32x16_bf16(a, b, c, 0, 0, 0); }
;     ...
;   for (int kt = 0; kt < nk; ++kt) {
;     if (kt + 1 < nk) { if (MI == 4) asm volatile("s_waitcnt vmcnt(6)" ::: "memory"); else asm volatile("s_waitcnt vmcnt(4)" ::: "memory"); } else asm volatile("s_waitcnt vmcnt(0)" ::: "memory");
;     __builtin_amdgcn_s_barrier();
;     if (kt + 2 < nk) { int s2 = stg + 2; if (s2 >= 3) s2 -= 3; g2_issue<MI>(ag + (size_t)(kt + 2) * 32, bg + (size_t)(kt + 2) * 32, lda, ldb, voffa, voffb, lds + s2 * G2_STAGE, w); }
;     const unsigned so = (unsigned)(stg * G2_STAGE);
;     __builtin_amdgcn_s_setprio(1);
; #pragma unroll
;     for (int ks = 0; ks < 2; ++ks) {
;       const unsigned aa = (ks ? la1 : la0) + so, bb = (ks ? lb1 : lb0) + so;
;       bf16x8 fb0, fb1, fa0, fa1, fa2, fa3;
;       asm volatile("ds_read_b128 %0, %1" : "=v"(fb0) : "v"(bb));
;       asm volatile("ds_read_b128 %0, %1 offset:2048" : "=v"(fb1) : "v"(bb));
;       asm volatile("ds_read_b128 %0, %1" : "=v"(fa0) : "v"(aa));
;       asm volatile("ds_read_b128 %0, %1 offset:2048" : "=v"(fa1) : "v"(aa));
;       if constexpr (MI == 4) {
;         asm volatile("ds_read_b128 %0, %1 offset:4096" : "=v"(fa2) : "v"(aa));
;         asm volatile("ds_read_b128 %0, %1 offset:6144" : "=v"(fa3) : "v"(aa));
;         __builtin_amdgcn_sched_barrier(0);
;         asm volatile("s_waitcnt lgkmcnt(3)" : "+v"(fb0), "+v"(fb1), "+v"(fa0));
;         acc[0][0][0] = mfma(fa0, fb0, acc[0][0][0]); acc[0][0][1] = mfma(fa0, fb1, acc[0][0][1]); __builtin_amdgcn_sched_barrier(0);
;         asm volatile("s_waitcnt lgkmcnt(2)" : "+v"(fa1));
;         acc[0][1][0] = mfma(fa1, fb0, acc[0][1][0]); acc[0][1][1] = mfma(fa1, fb1, acc[0][1][1]); __builtin_amdgcn_sched_barrier(0);
;         asm volatile("s_waitcnt lgkmcnt(1)" : "+v"(fa2));
;         acc[MI / 2 - 1][0][0] = mfma(fa2, fb0, acc[MI / 2 - 1][0][0]); acc[MI / 2 - 1][0][1] = mfma(fa2, fb1, acc[MI / 2 - 1][0][1]); __builtin_amdgcn_sched_barrier(0);
;         asm volatile("s_waitcnt lgkmcnt(0)" : "+v"(fa3));
;         acc[MI / 2 - 1][1][0] = mfma(fa3, fb0, acc[MI / 2 - 1][1][0]); acc[MI / 2 - 1][1][1] = mfma(fa3, fb1, acc[MI / 2 - 1][1][1]); __builtin_amdgcn_sched_barrier(0);
;       } else {
;         __builtin_amdgcn_sched_barrier(0);
;         asm volatile("s_waitcnt lgkmcnt(1)" : "+v"(fb0), "+v"(fb1), "+v"(fa0));
.Lhyt_afterF_tail:
	s_nop 0
	s_waitcnt lgkmcnt(1)
	s_nop 0
	v_mfma_f32_32x32x16_bf16 v[34:49], v[188:191], v[180:183], v[34:49]
	v_mfma_f32_32x32x16_bf16 v[50:65], v[188:191], v[184:187], v[50:65]
	s_waitcnt lgkmcnt(0)
	s_nop 0
	v_mfma_f32_32x32x16_bf16 v[18:33], v[242:245], v[180:183], v[18:33]
	v_mfma_f32_32x32x16_bf16 v[2:17], v[242:245], v[184:187], v[2:17]
.Lhyt_odd_tail:
	s_setprio 0
	s_add_i32 s98, s10, 1
	s_cmp_lg_u32 s10, 2
	s_cselect_b32 s10, s98, 0
	s_waitcnt vmcnt(4) lgkmcnt(0)
	s_barrier
	s_mul_i32 s99, s10, 0x6000
	s_setprio 1
	v_add_u32_e32 v73, s99, v67
	v_add_u32_e32 v90, s99, v68
	v_add_u32_e32 v86, v73, v71
	v_add_u32_e32 v78, v90, v71
	ds_read_b128 v[74:77], v78
	ds_read_b128 v[78:81], v78 offset:2048
	ds_read_b128 v[82:85], v86
	ds_read_b128 v[86:89], v86 offset:2048
	v_add_u32_e32 v238, v90, v69
	v_add_u32_e32 v73, v73, v69
	ds_read_b128 v[180:183], v238
	ds_read_b128 v[184:187], v238 offset:2048
	ds_read_b128 v[188:191], v73
	ds_read_b128 v[242:245], v73 offset:2048
	s_cmpk_eq_i32 s4, 0xf80
	s_cbranch_scc1 .Lhyt_noissueO_tail
	s_add_u32 s14, s2, s4
	s_addc_u32 s15, s3, s5
	s_add_u32 s12, s14, 0x80
	s_addc_u32 s13, s15, 0
	s_add_i32 s16, s11, s8
	s_mov_b32 m0, s16
	s_nop 0
	global_load_lds_dwordx4 v70, s[12:13]
	global_load_dwordx4 v[222:225], v70, s[12:13] offset:64
	s_nop 0
	s_waitcnt lgkmcnt(5)
	s_nop 0
	v_mfma_f32_32x32x16_bf16 v[34:49], v[82:85], v[74:77], v[34:49]
	v_mfma_f32_32x32x16_bf16 v[50:65], v[82:85], v[78:81], v[50:65]
	s_add_u32 s12, s14, 0x10080
	s_addc_u32 s13, s15, 0
	s_add_i32 s11, s11, s9
	s_mov_b32 m0, s11
	s_nop 0
	global_load_lds_dwordx4 v70, s[12:13]
	global_load_dwordx4 v[226:229], v70, s[12:13] offset:64
	s_waitcnt lgkmcnt(4)
	s_nop 0
	v_mfma_f32_32x32x16_bf16 v[18:33], v[86:89], v[74:77], v[18:33]
	v_mfma_f32_32x32x16_bf16 v[2:17], v[86:89], v[78:81], v[2:17]
	s_branch .Lhyt_afterO_tail

; DEV bf16_t f2bf(float f) { return (bf16_t)(cvtpk(f, 0.f) & 0xffffu); }
; DEV f32x16 mfma(bf16x8 a, bf16x8 b, f32x16 c) { return __builtin_amdgcn_mfma_f32_32x32x16_bf16(a, b, c, 0, 0, 0); }
;     ...
;         acc[0][1][0] = mfma(fa1, fb0, acc[0][1][0]); acc[0][1][1] = mfma(fa1, fb1, acc[0][1][1]); __builtin_amdgcn_sched_barrier(0);
;       }
;     }
;     __builtin_amdgcn_s_setprio(0);
;     stg = stg == 2 ? 0 : stg + 1;
;   }
;   __syncthreads();
;   DEV void operator()(f32x16 (&acc)[2][2], int mb, int nb, int r32, int hh) const {
; #pragma unroll
;     for (int mi = 0; mi < 2; ++mi)
; #pragma unroll
;       for (int ni = 0; ni < 2; ++ni)
; #pragma unroll
;         for (int r = 0; r < 16; ++r) {
;           int row = mb + mi * 32 + 8 * (r >> 2) + 4 * hh + (r & 3);
;           C[(size_t)row * ldc + nb + ni * 32 + r32] = f2bf(acc[mi][ni][r]);
;         }
;   }
.Lhyt_afterO_tail:
	s_nop 0
	s_waitcnt lgkmcnt(1)
	s_nop 0
	v_mfma_f32_32x32x16_bf16 v[34:49], v[188:191], v[180:183], v[34:49]
	v_mfma_f32_32x32x16_bf16 v[50:65], v[188:191], v[184:187], v[50:65]
	s_waitcnt lgkmcnt(0)
	s_nop 0
	v_mfma_f32_32x32x16_bf16 v[18:33], v[242:245], v[180:183], v[18:33]
	v_mfma_f32_32x32x16_bf16 v[2:17], v[242:245], v[184:187], v[2:17]
	s_add_i32 s98, s10, 1
	s_cmp_lg_u32 s10, 2
	s_cselect_b32 s10, s98, 0
	s_add_u32 s4, s4, 0x80
	s_addc_u32 s5, s5, 0
	s_cmpk_eq_i32 s4, 0x1000
	s_cbranch_scc0 .LBB0_122
	s_setprio 0
	v_readlane_b32 s0, v240, 59
	s_add_i32 s6, s6, s0
	v_readlane_b32 s0, v240, 60
	s_or_b32 s0, s7, s0
	s_lshl_b32 s0, s0, 1
	s_add_u32 s0, s24, s0
	v_lshl_or_b32 v84, v66, 2, s6
	s_addc_u32 s1, s25, 0
	v_lshlrev_b32_e32 v66, 1, v1
	v_mov_b32_e32 v67, v0
	v_lshl_add_u64 v[66:67], s[0:1], 0, v[66:67]
	v_cvt_pk_bf16_f32 v1, v34, s0
	v_mad_i64_i32 v[68:69], s[0:1], v84, s67, v[66:67]
	v_or_b32_e32 v34, 1, v84
	s_nop 0
	v_cvt_pk_bf16_f32 v85, v35, s0
	v_mad_i64_i32 v[34:35], s[0:1], v34, s67, v[66:67]
	v_or_b32_e32 v70, 2, v84
	s_nop 0
	v_cvt_pk_bf16_f32 v86, v36, s0
	v_mad_i64_i32 v[70:71], s[0:1], v70, s67, v[66:67]
	v_or_b32_e32 v36, 3, v84
	s_nop 0
	v_cvt_pk_bf16_f32 v87, v37, s0
	v_mad_i64_i32 v[36:37], s[0:1], v36, s67, v[66:67]
	v_or_b32_e32 v72, 8, v84
	s_nop 0
	v_cvt_pk_bf16_f32 v88, v38, s0
	v_mad_i64_i32 v[72:73], s[0:1], v72, s67, v[66:67]
	v_or_b32_e32 v38, 9, v84
	s_nop 0
	v_cvt_pk_bf16_f32 v89, v39, s0
	v_mad_i64_i32 v[38:39], s[0:1], v38, s67, v[66:67]
	v_or_b32_e32 v74, 10, v84
	s_nop 0
	v_cvt_pk_bf16_f32 v90, v40, s0
	v_mad_i64_i32 v[74:75], s[0:1], v74, s67, v[66:67]
	v_or_b32_e32 v40, 11, v84
	s_nop 0
	v_cvt_pk_bf16_f32 v91, v41, s0
	v_mad_i64_i32 v[40:41], s[0:1], v40, s67, v[66:67]
	v_or_b32_e32 v76, 16, v84
	s_nop 0
	v_cvt_pk_bf16_f32 v92, v42, s0
	v_mad_i64_i32 v[76:77], s[0:1], v76, s67, v[66:67]
	v_or_b32_e32 v42, 17, v84
	s_nop 0
	v_cvt_pk_bf16_f32 v93, v43, s0
	v_mad_i64_i32 v[42:43], s[0:1], v42, s67, v[66:67]
	v_or_b32_e32 v78, 18, v84
	s_nop 0
	v_cvt_pk_bf16_f32 v94, v44, s0
	v_mad_i64_i32 v[78:79], s[0:1], v78, s67, v[66:67]
	v_or_b32_e32 v44, 19, v84
	s_nop 0
	v_cvt_pk_bf16_f32 v95, v45, s0
	v_mad_i64_i32 v[44:45], s[0:1], v44, s67, v[66:67]
	v_or_b32_e32 v80, 24, v84
	s_nop 0
	v_cvt_pk_bf16_f32 v96, v46, s0
	v_mad_i64_i32 v[80:81], s[0:1], v80, s67, v[66:67]
	v_or_b32_e32 v46, 25, v84
	s_nop 0
	v_cvt_pk_bf16_f32 v97, v47, s0
	v_mad_i64_i32 v[46:47], s[0:1], v46, s67, v[66:67]
	v_or_b32_e32 v82, 26, v84
	s_nop 0
	v_cvt_pk_bf16_f32 v98, v48, s0
	v_mad_i64_i32 v[82:83], s[0:1], v82, s67, v[66:67]
	v_or_b32_e32 v48, 27, v84
	s_nop 0
	v_cvt_pk_bf16_f32 v99, v49, s0
	v_mad_i64_i32 v[48:49], s[0:1], v48, s67, v[66:67]
	s_waitcnt lgkmcnt(0)
	s_nop 0
	v_cvt_pk_bf16_f32 v100, v50, s0
	v_or_b32_e32 v50, 32, v84
	v_cvt_pk_bf16_f32 v101, v51, s0
	v_cvt_pk_bf16_f32 v102, v52, s0
	v_cvt_pk_bf16_f32 v103, v53, s0
	v_cvt_pk_bf16_f32 v104, v54, s0
	v_cvt_pk_bf16_f32 v105, v55, s0
	v_cvt_pk_bf16_f32 v106, v56, s0
	v_cvt_pk_bf16_f32 v107, v57, s0
	v_cvt_pk_bf16_f32 v108, v58, s0
	v_cvt_pk_bf16_f32 v109, v59, s0
	v_cvt_pk_bf16_f32 v110, v60, s0
	v_cvt_pk_bf16_f32 v111, v61, s0
	v_cvt_pk_bf16_f32 v112, v62, s0
	v_cvt_pk_bf16_f32 v113, v63, s0
	v_cvt_pk_bf16_f32 v114, v64, s0
	v_cvt_pk_bf16_f32 v115, v65, s0
	v_cvt_pk_bf16_f32 v116, v18, s0
	v_mad_i64_i32 v[50:51], s[0:1], v50, s67, v[66:67]
	v_or_b32_e32 v18, 33, v84
	s_nop 0
	v_cvt_pk_bf16_f32 v117, v19, s0
	v_mad_i64_i32 v[18:19], s[0:1], v18, s67, v[66:67]
	v_or_b32_e32 v52, 34, v84
	s_nop 0
	v_cvt_pk_bf16_f32 v118, v20, s0
	v_mad_i64_i32 v[52:53], s[0:1], v52, s67, v[66:67]
	v_or_b32_e32 v20, 35, v84
	s_nop 0
	v_cvt_pk_bf16_f32 v119, v21, s0
	v_mad_i64_i32 v[20:21], s[0:1], v20, s67, v[66:67]
	v_or_b32_e32 v54, 40, v84
	s_nop 0
	v_cvt_pk_bf16_f32 v120, v22, s0
	v_mad_i64_i32 v[54:55], s[0:1], v54, s67, v[66:67]
	v_or_b32_e32 v22, 41, v84
	s_nop 0
	v_cvt_pk_bf16_f32 v121, v23, s0
	v_mad_i64_i32 v[22:23], s[0:1], v22, s67, v[66:67]
	v_or_b32_e32 v56, 42, v84
	s_nop 0
	v_cvt_pk_bf16_f32 v122, v24, s0
	v_mad_i64_i32 v[56:57], s[0:1], v56, s67, v[66:67]
	v_or_b32_e32 v24, 43, v84
	s_nop 0
	v_cvt_pk_bf16_f32 v123, v25, s0
	v_mad_i64_i32 v[24:25], s[0:1], v24, s67, v[66:67]
	v_or_b32_e32 v58, 48, v84
	s_nop 0
	v_cvt_pk_bf16_f32 v124, v26, s0
	v_mad_i64_i32 v[58:59], s[0:1], v58, s67, v[66:67]
	v_or_b32_e32 v26, 49, v84
	s_nop 0
	v_cvt_pk_bf16_f32 v125, v27, s0
	v_mad_i64_i32 v[26:27], s[0:1], v26, s67, v[66:67]
	v_or_b32_e32 v60, 50, v84
	s_nop 0
	v_cvt_pk_bf16_f32 v126, v28, s0
	v_mad_i64_i32 v[60:61], s[0:1], v60, s67, v[66:67]
	v_or_b32_e32 v28, 51, v84
	s_nop 0
	v_cvt_pk_bf16_f32 v127, v29, s0
	v_mad_i64_i32 v[28:29], s[0:1], v28, s67, v[66:67]
	v_or_b32_e32 v62, 56, v84
	s_nop 0
	v_cvt_pk_bf16_f32 v128, v30, s0
	v_mad_i64_i32 v[62:63], s[0:1], v62, s67, v[66:67]
	v_or_b32_e32 v30, 57, v84
	s_nop 0
	v_cvt_pk_bf16_f32 v129, v31, s0
	v_mad_i64_i32 v[30:31], s[0:1], v30, s67, v[66:67]
	v_or_b32_e32 v64, 58, v84
	s_nop 0
	v_cvt_pk_bf16_f32 v130, v32, s0
	v_mad_i64_i32 v[64:65], s[0:1], v64, s67, v[66:67]
	v_or_b32_e32 v32, 59, v84
	s_nop 0
	v_cvt_pk_bf16_f32 v84, v33, s0
	v_mad_i64_i32 v[32:33], s[0:1], v32, s67, v[66:67]
	s_barrier
; DEV bf16_t f2bf(float f) { return (bf16_t)(cvtpk(f, 0.f) & 0xffffu); }
;   DEV void operator()(f32x16 (&acc)[2][2], int mb, int nb, int r32, int hh) const {
; #pragma unroll
;     for (int mi = 0; mi < 2; ++mi)
; #pragma unroll
;       for (int ni = 0; ni < 2; ++ni)
; #pragma unroll
;         for (int r = 0; r < 16; ++r) {
;           int row = mb + mi * 32 + 8 * (r >> 2) + 4 * hh + (r & 3);
;           C[(size_t)row * ldc + nb + ni * 32 + r32] = f2bf(acc[mi][ni][r]);
;         }
;   }
	s_nop 0
	v_cvt_pk_bf16_f32 v2, v2, s0
	v_cvt_pk_bf16_f32 v3, v3, s0
	v_cvt_pk_bf16_f32 v4, v4, s0
	v_cvt_pk_bf16_f32 v5, v5, s0
	v_cvt_pk_bf16_f32 v6, v6, s0
	v_cvt_pk_bf16_f32 v7, v7, s0
	v_cvt_pk_bf16_f32 v8, v8, s0
	v_cvt_pk_bf16_f32 v9, v9, s0
	v_cvt_pk_bf16_f32 v10, v10, s0
	v_cvt_pk_bf16_f32 v11, v11, s0
	v_cvt_pk_bf16_f32 v12, v12, s0
	v_cvt_pk_bf16_f32 v13, v13, s0
	v_cvt_pk_bf16_f32 v14, v14, s0
	v_cvt_pk_bf16_f32 v15, v15, s0
	v_cvt_pk_bf16_f32 v16, v16, s0
	v_cvt_pk_bf16_f32 v17, v17, s0
	global_store_short v[68:69], v1, off
	global_store_short v[34:35], v85, off
	global_store_short v[70:71], v86, off
	global_store_short v[36:37], v87, off
	global_store_short v[72:73], v88, off
	global_store_short v[38:39], v89, off
	global_store_short v[74:75], v90, off
	global_store_short v[40:41], v91, off
	global_store_short v[76:77], v92, off
	global_store_short v[42:43], v93, off
	global_store_short v[78:79], v94, off
	global_store_short v[44:45], v95, off
	global_store_short v[80:81], v96, off
	global_store_short v[46:47], v97, off
	global_store_short v[82:83], v98, off
	global_store_short v[48:49], v99, off
	global_store_short v[68:69], v100, off offset:64
	global_store_short v[34:35], v101, off offset:64
	global_store_short v[70:71], v102, off offset:64
	global_store_short v[36:37], v103, off offset:64
	global_store_short v[72:73], v104, off offset:64
	global_store_short v[38:39], v105, off offset:64
	global_store_short v[74:75], v106, off offset:64
	global_store_short v[40:41], v107, off offset:64
	global_store_short v[76:77], v108, off offset:64
	global_store_short v[42:43], v109, off offset:64
	global_store_short v[78:79], v110, off offset:64
	global_store_short v[44:45], v111, off offset:64
	global_store_short v[80:81], v112, off offset:64
	global_store_short v[46:47], v113, off offset:64
	global_store_short v[82:83], v114, off offset:64
	global_store_short v[48:49], v115, off offset:64
	global_store_short v[50:51], v116, off
	global_store_short v[18:19], v117, off
	global_store_short v[52:53], v118, off
	global_store_short v[20:21], v119, off
	global_store_short v[54:55], v120, off
	global_store_short v[22:23], v121, off
	global_store_short v[56:57], v122, off
	global_store_short v[24:25], v123, off
	global_store_short v[58:59], v124, off
	global_store_short v[26:27], v125, off
	global_store_short v[60:61], v126, off
	global_store_short v[28:29], v127, off
	global_store_short v[62:63], v128, off
	global_store_short v[30:31], v129, off
	global_store_short v[64:65], v130, off
	global_store_short v[32:33], v84, off
	global_store_short v[50:51], v2, off offset:64
	global_store_short v[18:19], v3, off offset:64
	global_store_short v[52:53], v4, off offset:64
	global_store_short v[20:21], v5, off offset:64
	global_store_short v[54:55], v6, off offset:64
	global_store_short v[22:23], v7, off offset:64
	global_store_short v[56:57], v8, off offset:64
	global_store_short v[24:25], v9, off offset:64
	global_store_short v[58:59], v10, off offset:64
	global_store_short v[26:27], v11, off offset:64
	global_store_short v[60:61], v12, off offset:64
	global_store_short v[28:29], v13, off offset:64
	global_store_short v[62:63], v14, off offset:64
	global_store_short v[30:31], v15, off offset:64
	global_store_short v[64:65], v16, off offset:64
	global_store_short v[32:33], v17, off offset:64
